# speedup vs baseline: 1.0059x; 1.0018x over previous
; DI unsigned cvtpk(float lo, float hi) { f32x2_t v = {lo, hi}; bf16x2_t b = __builtin_convertvector(v, bf16x2_t); return __builtin_bit_cast(unsigned, b); }
; __global__ void __launch_bounds__(NTHR, 2) mega_fwd(Params P) {
;     ...
;                 for (size_t e = t0; e < (size_t)8 * PAST * 32; e += tn) {
;                     const size_t row = e >> 5; const int c8 = (int)(e & 31) * 8; const int b = (int)(row >> 12), t = (int)(row & 4095);
;                     const f32x4 a = *(const f32x4*)(cck + row * 256 + c8), b4 = *(const f32x4*)(cck + row * 256 + c8 + 4);
;                     u32x4 w; w.x = cvtpk(a.x, a.y); w.y = cvtpk(a.z, a.w); w.z = cvtpk(b4.x, b4.y); w.w = cvtpk(b4.z, b4.w);
;                     *(u32x4*)(CKVB + ((size_t)MP + (size_t)b * SKV_S + t) * 256 + c8) = w;
;                 }
.LBB0_471:
	v_lshrrev_b64 v[10:11], 5, v[8:9]
	v_and_b32_e32 v20, 0xf8, v6
	v_lshlrev_b64 v[10:11], 10, v[10:11]
	v_lshl_add_u64 v[10:11], s[40:41], 0, v[10:11]
	v_lshlrev_b32_e32 v12, 2, v20
	v_mov_b32_e32 v13, v0
	v_lshl_add_u64 v[14:15], v[10:11], 0, v[12:13]
	global_load_dwordx4 v[10:13], v[14:15], off offset:16 nt
	s_nop 0
	global_load_dwordx4 v[14:17], v[14:15], off nt
	v_alignbit_b32 v1, v9, v8, 5
	v_and_b32_e32 v18, 0xfff, v1
	v_mov_b32_e32 v19, v0
	v_alignbit_b32 v1, v9, v8, 17
	v_lshl_add_u64 v[8:9], v[8:9], 0, s[8:9]
	v_lshl_add_u64 v[6:7], v[6:7], 0, s[54:55]
	s_waitcnt vmcnt(0)
	v_cvt_pk_bf16_f32 v14, v14, v15
	v_cvt_pk_bf16_f32 v15, v16, v17
	v_cvt_pk_bf16_f32 v16, v10, v11
	v_mad_u64_u32 v[10:11], s[4:5], v1, s6, v[18:19]
	v_lshlrev_b64 v[10:11], 9, v[10:11]
	v_cvt_pk_bf16_f32 v17, v12, v13
	v_lshl_add_u64 v[10:11], s[50:51], 0, v[10:11]
	v_lshlrev_b32_e32 v12, 1, v20
	v_mov_b32_e32 v13, v0
	v_lshl_add_u64 v[10:11], v[10:11], 0, v[12:13]
	v_add_co_u32_e32 v10, vcc, 0x1000000, v10
	s_mov_b64 s[4:5], 0xfffff
	s_nop 0
	v_addc_co_u32_e32 v11, vcc, 0, v11, vcc
	v_cmp_lt_u64_e32 vcc, s[4:5], v[8:9]
	s_or_b64 s[52:53], vcc, s[52:53]
	global_store_dwordx4 v[10:11], v[14:17], off nt
	s_andn2_b64 exec, exec, s[52:53]
	s_cbranch_execnz .LBB0_471

; DI unsigned cvtpk(float lo, float hi) { f32x2_t v = {lo, hi}; bf16x2_t b = __builtin_convertvector(v, bf16x2_t); return __builtin_bit_cast(unsigned, b); }
; __global__ void __launch_bounds__(NTHR, 2) mega_fwd(Params P) {
;     ...
;                 for (size_t e = t0; e < (size_t)8 * PAST * 4; e += tn) {
;                     const size_t row = e >> 2; const int c8 = (int)(e & 3) * 8; const int b = (int)(row >> 12), t = (int)(row & 4095);
;                     const f32x4 a = *(const f32x4*)(ckr + row * 32 + c8), b4 = *(const f32x4*)(ckr + row * 32 + c8 + 4);
;                     u32x4 w; w.x = cvtpk(a.x, a.y); w.y = cvtpk(a.z, a.w); w.z = cvtpk(b4.x, b4.y); w.w = cvtpk(b4.z, b4.w);
;                     *(u32x4*)(KR + ((size_t)MP + (size_t)b * SKV_S + t) * 32 + c8) = w;
;                 }
.LBB0_474:
	v_lshrrev_b64 v[6:7], 2, v[2:3]
	v_and_b32_e32 v16, 24, v4
	v_lshlrev_b64 v[6:7], 7, v[6:7]
	v_lshl_add_u64 v[6:7], s[34:35], 0, v[6:7]
	v_lshlrev_b32_e32 v8, 2, v16
	v_mov_b32_e32 v9, v0
	v_lshl_add_u64 v[10:11], v[6:7], 0, v[8:9]
	global_load_dwordx4 v[6:9], v[10:11], off offset:16 nt
	s_nop 0
	global_load_dwordx4 v[10:13], v[10:11], off nt
	v_alignbit_b32 v1, v3, v2, 2
	v_and_b32_e32 v14, 0xfff, v1
	v_mov_b32_e32 v15, v0
	v_alignbit_b32 v1, v3, v2, 14
	v_lshl_add_u64 v[2:3], v[2:3], 0, s[8:9]
	v_lshl_add_u64 v[4:5], v[4:5], 0, s[48:49]
	s_waitcnt vmcnt(0)
	v_cvt_pk_bf16_f32 v10, v10, v11
	v_cvt_pk_bf16_f32 v11, v12, v13
	v_cvt_pk_bf16_f32 v12, v6, v7
	v_mad_u64_u32 v[6:7], s[4:5], v1, s6, v[14:15]
	v_lshlrev_b64 v[6:7], 6, v[6:7]
	v_cvt_pk_bf16_f32 v13, v8, v9
	v_lshl_add_u64 v[6:7], s[46:47], 0, v[6:7]
	v_lshlrev_b32_e32 v8, 1, v16
	v_mov_b32_e32 v9, v0
	v_lshl_add_u64 v[6:7], v[6:7], 0, v[8:9]
	v_add_co_u32_e32 v6, vcc, 0x200000, v6
	s_mov_b64 s[4:5], 0x1ffff
	s_nop 0
	v_addc_co_u32_e32 v7, vcc, 0, v7, vcc
	v_cmp_lt_u64_e32 vcc, s[4:5], v[2:3]
	s_or_b64 s[42:43], vcc, s[42:43]
	global_store_dwordx4 v[6:7], v[10:13], off nt
	s_andn2_b64 exec, exec, s[42:43]
	s_cbranch_execnz .LBB0_474
